# attention softmax: lazy running-max update (rescale only when the tile max exceeds the running max by 8 in log2 units) + row max via v_max3 tree
# speedup vs baseline: 1.0135x; 1.0023x over previous
; __device__ __forceinline__ void attn_tile(const LAS bf16_t* kl, unsigned vaddr, int kt, const bf16x8 (&qf)[8], f32x16 (&o)[4], float& mrun, float& lrun, int r, int h, int rr, int p, int hd, size_t qtok,
;                                           bf16_t* __restrict__ OP, float* __restrict__ LSE) {
;     ...
;     float mx = fmaxf(fmaxf(s[0], s[1]), fmaxf(s[2], s[3]));
; #pragma unroll
;     for (int i = 4; i < 16; i += 4) mx = fmaxf(mx, fmaxf(fmaxf(s[i], s[i + 1]), fmaxf(s[i + 2], s[i + 3])));
;     { const auto pr = __builtin_amdgcn_permlane32_swap(__float_as_uint(mx), __float_as_uint(mx), false, false); mx = fmaxf(__uint_as_float(pr[0]), __uint_as_float(pr[1])); }
;     const float mnew = fmaxf(mrun, mx * scl);
;     const float alpha = __builtin_amdgcn_exp2f(mrun - mnew);
;     float rs = 0.f;
; #pragma unroll
;     for (int i = 0; i < 16; ++i) { s[i] = __builtin_amdgcn_exp2f(__builtin_fmaf(s[i], scl, -mnew)); rs += s[i]; }
;     { const auto pr = __builtin_amdgcn_permlane32_swap(__float_as_uint(rs), __float_as_uint(rs), false, false); rs = __uint_as_float(pr[0]) + __uint_as_float(pr[1]); }
;     lrun = lrun * alpha + rs; mrun = mnew;
;     if (__builtin_amdgcn_readfirstlane(__any(alpha != 1.0f) ? 1 : 0)) {
; #pragma unroll
;         for (int dt = 0; dt < 4; ++dt)
; #pragma unroll
;             for (int i = 0; i < 16; ++i) o[dt][i] *= alpha;
;     }
.LBB0_526:
	v_max3_f32 v1, v108, v109, v106
	v_max3_f32 v14, v107, v103, v101
	v_max3_f32 v15, v105, v99, v98
	v_max3_f32 v80, v100, v94, v95
	v_max3_f32 v1, v1, v104, v102
	v_max3_f32 v14, v14, v97, v96
	v_max3_f32 v1, v1, v14, v15
	v_max_f32_e32 v1, v1, v80
	v_mov_b32_e32 v14, v1
	s_nop 1
	v_permlane32_swap_b32_e32 v1, v14
	v_max_f32_e32 v1, v1, v14
	v_mul_f32_e32 v1, 0x3e0293ee, v1
	v_max_f32_e32 v14, v187, v187
	v_add_f32_e32 v80, 0x41000000, v14
	v_cmp_gt_f32_e32 vcc, v1, v80
	s_nop 1
	v_cndmask_b32_e32 v1, v14, v1, vcc
	v_fma_f32 v14, v109, s74, -v1
	v_exp_f32_e32 v89, v14
	v_fma_f32 v80, v108, s74, -v1
	v_exp_f32_e32 v90, v80
	v_fma_f32 v80, v107, s74, -v1
	v_exp_f32_e32 v91, v80
	v_fma_f32 v80, v106, s74, -v1
	v_exp_f32_e32 v92, v80
	v_fma_f32 v80, v105, s74, -v1
	v_add_f32_e32 v15, 0, v89
	v_exp_f32_e32 v93, v80
	v_fma_f32 v80, v99, s74, -v1
	v_add_f32_e32 v15, v90, v15
	v_exp_f32_e32 v99, v80
	v_fma_f32 v80, v101, s74, -v1
	v_add_f32_e32 v15, v91, v15
	v_exp_f32_e32 v101, v80
	v_fma_f32 v80, v103, s74, -v1
	v_add_f32_e32 v15, v92, v15
	v_exp_f32_e32 v103, v80
	v_fma_f32 v80, v104, s74, -v1
	v_add_f32_e32 v15, v93, v15
	v_exp_f32_e32 v81, v80
	v_fma_f32 v80, v102, s74, -v1
	v_add_f32_e32 v15, v99, v15
	v_exp_f32_e32 v82, v80
	v_fma_f32 v80, v100, s74, -v1
	v_add_f32_e32 v15, v101, v15
	v_exp_f32_e32 v83, v80
	v_fma_f32 v80, v98, s74, -v1
	v_sub_f32_e32 v14, v187, v1
	v_add_f32_e32 v15, v103, v15
	v_exp_f32_e32 v84, v80
	v_fma_f32 v80, v97, s74, -v1
	v_add_f32_e32 v15, v81, v15
	v_exp_f32_e32 v85, v80
	v_fma_f32 v80, v96, s74, -v1
	v_exp_f32_e32 v14, v14
	v_add_f32_e32 v15, v82, v15
	v_exp_f32_e32 v86, v80
	v_fma_f32 v80, v95, s74, -v1
	v_add_f32_e32 v15, v83, v15
	v_exp_f32_e32 v87, v80
	v_fma_f32 v80, v94, s74, -v1
	v_add_f32_e32 v15, v84, v15
	v_exp_f32_e32 v88, v80
	v_add_f32_e32 v15, v85, v15
	v_cmp_neq_f32_e32 vcc, 1.0, v14
	v_add_f32_e32 v15, v86, v15
	s_cmp_lg_u64 vcc, 0
	v_add_f32_e32 v15, v87, v15
	s_cselect_b64 s[38:39], -1, 0
	v_add_f32_e32 v15, v88, v15
	v_cndmask_b32_e64 v94, 0, 1, s[38:39]
	v_mov_b32_e32 v80, v15
	v_readfirstlane_b32 s33, v94
	s_bitcmp0_b32 s33, 0
	v_permlane32_swap_b32_e32 v15, v80
	s_cbranch_scc1 .LBB0_528
	v_pk_mul_f32 v[78:79], v[78:79], v[14:15] op_sel_hi:[1,0]
	v_pk_mul_f32 v[76:77], v[76:77], v[14:15] op_sel_hi:[1,0]
	v_pk_mul_f32 v[74:75], v[74:75], v[14:15] op_sel_hi:[1,0]
	v_pk_mul_f32 v[72:73], v[72:73], v[14:15] op_sel_hi:[1,0]
	v_pk_mul_f32 v[70:71], v[70:71], v[14:15] op_sel_hi:[1,0]
	v_pk_mul_f32 v[68:69], v[68:69], v[14:15] op_sel_hi:[1,0]
	v_pk_mul_f32 v[66:67], v[66:67], v[14:15] op_sel_hi:[1,0]
	v_pk_mul_f32 v[64:65], v[64:65], v[14:15] op_sel_hi:[1,0]
	v_pk_mul_f32 v[62:63], v[62:63], v[14:15] op_sel_hi:[1,0]
	v_pk_mul_f32 v[60:61], v[60:61], v[14:15] op_sel_hi:[1,0]
	v_pk_mul_f32 v[58:59], v[58:59], v[14:15] op_sel_hi:[1,0]
	v_pk_mul_f32 v[56:57], v[56:57], v[14:15] op_sel_hi:[1,0]
	v_pk_mul_f32 v[54:55], v[54:55], v[14:15] op_sel_hi:[1,0]
	v_pk_mul_f32 v[52:53], v[52:53], v[14:15] op_sel_hi:[1,0]
	v_pk_mul_f32 v[50:51], v[50:51], v[14:15] op_sel_hi:[1,0]
	v_pk_mul_f32 v[48:49], v[48:49], v[14:15] op_sel_hi:[1,0]
	v_pk_mul_f32 v[46:47], v[46:47], v[14:15] op_sel_hi:[1,0]
	v_pk_mul_f32 v[44:45], v[44:45], v[14:15] op_sel_hi:[1,0]
	v_pk_mul_f32 v[42:43], v[42:43], v[14:15] op_sel_hi:[1,0]
	v_pk_mul_f32 v[40:41], v[40:41], v[14:15] op_sel_hi:[1,0]
	v_pk_mul_f32 v[38:39], v[38:39], v[14:15] op_sel_hi:[1,0]
	v_pk_mul_f32 v[36:37], v[36:37], v[14:15] op_sel_hi:[1,0]
	v_pk_mul_f32 v[34:35], v[34:35], v[14:15] op_sel_hi:[1,0]
	v_pk_mul_f32 v[32:33], v[32:33], v[14:15] op_sel_hi:[1,0]
	v_pk_mul_f32 v[30:31], v[30:31], v[14:15] op_sel_hi:[1,0]
	v_pk_mul_f32 v[28:29], v[28:29], v[14:15] op_sel_hi:[1,0]
	v_pk_mul_f32 v[26:27], v[26:27], v[14:15] op_sel_hi:[1,0]
	v_pk_mul_f32 v[24:25], v[24:25], v[14:15] op_sel_hi:[1,0]
	v_pk_mul_f32 v[22:23], v[22:23], v[14:15] op_sel_hi:[1,0]
	v_pk_mul_f32 v[20:21], v[20:21], v[14:15] op_sel_hi:[1,0]
	v_pk_mul_f32 v[18:19], v[18:19], v[14:15] op_sel_hi:[1,0]
	v_pk_mul_f32 v[16:17], v[16:17], v[14:15] op_sel_hi:[1,0]

; __device__ __forceinline__ void attn_tile(const LAS bf16_t* kl, unsigned vaddr, int kt, const bf16x8 (&qf)[8], f32x16 (&o)[4], float& mrun, float& lrun, int r, int h, int rr, int p, int hd, size_t qtok,
;                                           bf16_t* __restrict__ OP, float* __restrict__ LSE) {
;     ...
;     float mx = fmaxf(fmaxf(s[0], s[1]), fmaxf(s[2], s[3]));
; #pragma unroll
;     for (int i = 4; i < 16; i += 4) mx = fmaxf(mx, fmaxf(fmaxf(s[i], s[i + 1]), fmaxf(s[i + 2], s[i + 3])));
;     { const auto pr = __builtin_amdgcn_permlane32_swap(__float_as_uint(mx), __float_as_uint(mx), false, false); mx = fmaxf(__uint_as_float(pr[0]), __uint_as_float(pr[1])); }
;     const float mnew = fmaxf(mrun, mx * scl);
;     const float alpha = __builtin_amdgcn_exp2f(mrun - mnew);
;     float rs = 0.f;
; #pragma unroll
;     for (int i = 0; i < 16; ++i) { s[i] = __builtin_amdgcn_exp2f(__builtin_fmaf(s[i], scl, -mnew)); rs += s[i]; }
;     { const auto pr = __builtin_amdgcn_permlane32_swap(__float_as_uint(rs), __float_as_uint(rs), false, false); rs = __uint_as_float(pr[0]) + __uint_as_float(pr[1]); }
;     lrun = lrun * alpha + rs; mrun = mnew;
;     if (__builtin_amdgcn_readfirstlane(__any(alpha != 1.0f) ? 1 : 0)) {
; #pragma unroll
;         for (int dt = 0; dt < 4; ++dt)
; #pragma unroll
;             for (int i = 0; i < 16; ++i) o[dt][i] *= alpha;
;     }
.LBB0_549:
	v_max3_f32 v1, v108, v109, v106
	v_max3_f32 v14, v107, v103, v101
	v_max3_f32 v15, v105, v99, v98
	v_max3_f32 v80, v100, v94, v95
	v_max3_f32 v1, v1, v104, v102
	v_max3_f32 v14, v14, v97, v96
	v_max3_f32 v1, v1, v14, v15
	v_max_f32_e32 v1, v1, v80
	v_mov_b32_e32 v14, v1
	s_nop 1
	v_permlane32_swap_b32_e32 v1, v14
	v_max_f32_e32 v1, v1, v14
	v_mul_f32_e32 v1, 0x3e0293ee, v1
	v_max_f32_e32 v14, v187, v187
	v_add_f32_e32 v80, 0x41000000, v14
	v_cmp_gt_f32_e32 vcc, v1, v80
	s_nop 1
	v_cndmask_b32_e32 v1, v14, v1, vcc
	v_fma_f32 v14, v109, s74, -v1
	v_exp_f32_e32 v89, v14
	v_fma_f32 v80, v108, s74, -v1
	v_exp_f32_e32 v90, v80
	v_fma_f32 v80, v107, s74, -v1
	v_exp_f32_e32 v91, v80
	v_fma_f32 v80, v106, s74, -v1
	v_exp_f32_e32 v92, v80
	v_fma_f32 v80, v105, s74, -v1
	v_add_f32_e32 v15, 0, v89
	v_exp_f32_e32 v93, v80
	v_fma_f32 v80, v99, s74, -v1
	v_add_f32_e32 v15, v90, v15
	v_exp_f32_e32 v99, v80
	v_fma_f32 v80, v101, s74, -v1
	v_add_f32_e32 v15, v91, v15
	v_exp_f32_e32 v101, v80
	v_fma_f32 v80, v103, s74, -v1
	v_add_f32_e32 v15, v92, v15
	v_exp_f32_e32 v103, v80
	v_fma_f32 v80, v104, s74, -v1
	v_add_f32_e32 v15, v93, v15
	v_exp_f32_e32 v81, v80
	v_fma_f32 v80, v102, s74, -v1
	v_add_f32_e32 v15, v99, v15
	v_exp_f32_e32 v82, v80
	v_fma_f32 v80, v100, s74, -v1
	v_add_f32_e32 v15, v101, v15
	v_exp_f32_e32 v83, v80
	v_fma_f32 v80, v98, s74, -v1
	v_sub_f32_e32 v14, v187, v1
	v_add_f32_e32 v15, v103, v15
	v_exp_f32_e32 v84, v80
	v_fma_f32 v80, v97, s74, -v1
	v_add_f32_e32 v15, v81, v15
	v_exp_f32_e32 v85, v80
	v_fma_f32 v80, v96, s74, -v1
	v_exp_f32_e32 v14, v14
	v_add_f32_e32 v15, v82, v15
	v_exp_f32_e32 v86, v80
	v_fma_f32 v80, v95, s74, -v1
	v_add_f32_e32 v15, v83, v15
	v_exp_f32_e32 v87, v80
	v_fma_f32 v80, v94, s74, -v1
	v_add_f32_e32 v15, v84, v15
	v_exp_f32_e32 v88, v80
	v_add_f32_e32 v15, v85, v15
	v_cmp_neq_f32_e32 vcc, 1.0, v14
	v_add_f32_e32 v15, v86, v15
	s_cmp_lg_u64 vcc, 0
	v_add_f32_e32 v15, v87, v15
	s_cselect_b64 s[36:37], -1, 0
	v_add_f32_e32 v15, v88, v15
	v_cndmask_b32_e64 v94, 0, 1, s[36:37]
	v_mov_b32_e32 v80, v15
	v_readfirstlane_b32 s33, v94
	s_bitcmp0_b32 s33, 0
	v_permlane32_swap_b32_e32 v15, v80
	s_cbranch_scc1 .LBB0_551
	v_pk_mul_f32 v[78:79], v[78:79], v[14:15] op_sel_hi:[1,0]
	v_pk_mul_f32 v[76:77], v[76:77], v[14:15] op_sel_hi:[1,0]
	v_pk_mul_f32 v[74:75], v[74:75], v[14:15] op_sel_hi:[1,0]
	v_pk_mul_f32 v[72:73], v[72:73], v[14:15] op_sel_hi:[1,0]
	v_pk_mul_f32 v[70:71], v[70:71], v[14:15] op_sel_hi:[1,0]
	v_pk_mul_f32 v[68:69], v[68:69], v[14:15] op_sel_hi:[1,0]
	v_pk_mul_f32 v[66:67], v[66:67], v[14:15] op_sel_hi:[1,0]
	v_pk_mul_f32 v[64:65], v[64:65], v[14:15] op_sel_hi:[1,0]
	v_pk_mul_f32 v[62:63], v[62:63], v[14:15] op_sel_hi:[1,0]
	v_pk_mul_f32 v[60:61], v[60:61], v[14:15] op_sel_hi:[1,0]
	v_pk_mul_f32 v[58:59], v[58:59], v[14:15] op_sel_hi:[1,0]
	v_pk_mul_f32 v[56:57], v[56:57], v[14:15] op_sel_hi:[1,0]
	v_pk_mul_f32 v[54:55], v[54:55], v[14:15] op_sel_hi:[1,0]
	v_pk_mul_f32 v[52:53], v[52:53], v[14:15] op_sel_hi:[1,0]
	v_pk_mul_f32 v[50:51], v[50:51], v[14:15] op_sel_hi:[1,0]
	v_pk_mul_f32 v[48:49], v[48:49], v[14:15] op_sel_hi:[1,0]
	v_pk_mul_f32 v[46:47], v[46:47], v[14:15] op_sel_hi:[1,0]
	v_pk_mul_f32 v[44:45], v[44:45], v[14:15] op_sel_hi:[1,0]
	v_pk_mul_f32 v[42:43], v[42:43], v[14:15] op_sel_hi:[1,0]
	v_pk_mul_f32 v[40:41], v[40:41], v[14:15] op_sel_hi:[1,0]
	v_pk_mul_f32 v[38:39], v[38:39], v[14:15] op_sel_hi:[1,0]
	v_pk_mul_f32 v[36:37], v[36:37], v[14:15] op_sel_hi:[1,0]
	v_pk_mul_f32 v[34:35], v[34:35], v[14:15] op_sel_hi:[1,0]
	v_pk_mul_f32 v[32:33], v[32:33], v[14:15] op_sel_hi:[1,0]
	v_pk_mul_f32 v[30:31], v[30:31], v[14:15] op_sel_hi:[1,0]
	v_pk_mul_f32 v[28:29], v[28:29], v[14:15] op_sel_hi:[1,0]
	v_pk_mul_f32 v[26:27], v[26:27], v[14:15] op_sel_hi:[1,0]
	v_pk_mul_f32 v[24:25], v[24:25], v[14:15] op_sel_hi:[1,0]
	v_pk_mul_f32 v[22:23], v[22:23], v[14:15] op_sel_hi:[1,0]
	v_pk_mul_f32 v[20:21], v[20:21], v[14:15] op_sel_hi:[1,0]
	v_pk_mul_f32 v[18:19], v[18:19], v[14:15] op_sel_hi:[1,0]
	v_pk_mul_f32 v[16:17], v[16:17], v[14:15] op_sel_hi:[1,0]

; __device__ __forceinline__ void attn_tile(const LAS bf16_t* kl, unsigned vaddr, int kt, const bf16x8 (&qf)[8], f32x16 (&o)[4], float& mrun, float& lrun, int r, int h, int rr, int p, int hd, size_t qtok,
;                                           bf16_t* __restrict__ OP, float* __restrict__ LSE) {
;     ...
;     float mx = fmaxf(fmaxf(s[0], s[1]), fmaxf(s[2], s[3]));
; #pragma unroll
;     for (int i = 4; i < 16; i += 4) mx = fmaxf(mx, fmaxf(fmaxf(s[i], s[i + 1]), fmaxf(s[i + 2], s[i + 3])));
;     { const auto pr = __builtin_amdgcn_permlane32_swap(__float_as_uint(mx), __float_as_uint(mx), false, false); mx = fmaxf(__uint_as_float(pr[0]), __uint_as_float(pr[1])); }
;     const float mnew = fmaxf(mrun, mx * scl);
;     const float alpha = __builtin_amdgcn_exp2f(mrun - mnew);
;     float rs = 0.f;
; #pragma unroll
;     for (int i = 0; i < 16; ++i) { s[i] = __builtin_amdgcn_exp2f(__builtin_fmaf(s[i], scl, -mnew)); rs += s[i]; }
;     { const auto pr = __builtin_amdgcn_permlane32_swap(__float_as_uint(rs), __float_as_uint(rs), false, false); rs = __uint_as_float(pr[0]) + __uint_as_float(pr[1]); }
;     lrun = lrun * alpha + rs; mrun = mnew;
;     if (__builtin_amdgcn_readfirstlane(__any(alpha != 1.0f) ? 1 : 0)) {
; #pragma unroll
;         for (int dt = 0; dt < 4; ++dt)
; #pragma unroll
;             for (int i = 0; i < 16; ++i) o[dt][i] *= alpha;
;     }
.LBB0_587:
	v_max3_f32 v1, v108, v109, v106
	v_max3_f32 v14, v107, v103, v101
	v_max3_f32 v15, v105, v99, v98
	v_max3_f32 v80, v100, v94, v95
	v_max3_f32 v1, v1, v104, v102
	v_max3_f32 v14, v14, v97, v96
	v_max3_f32 v1, v1, v14, v15
	v_max_f32_e32 v1, v1, v80
	v_mov_b32_e32 v14, v1
	s_nop 1
	v_permlane32_swap_b32_e32 v1, v14
	v_max_f32_e32 v1, v1, v14
	v_mul_f32_e32 v1, 0x3e0293ee, v1
	v_max_f32_e32 v14, v183, v183
	v_add_f32_e32 v80, 0x41000000, v14
	v_cmp_gt_f32_e32 vcc, v1, v80
	s_nop 1
	v_cndmask_b32_e32 v1, v14, v1, vcc
	v_fma_f32 v14, v109, s43, -v1
	v_exp_f32_e32 v89, v14
	v_fma_f32 v80, v108, s43, -v1
	v_exp_f32_e32 v90, v80
	v_fma_f32 v80, v107, s43, -v1
	v_exp_f32_e32 v91, v80
	v_fma_f32 v80, v106, s43, -v1
	v_exp_f32_e32 v92, v80
	v_fma_f32 v80, v105, s43, -v1
	v_add_f32_e32 v15, 0, v89
	v_exp_f32_e32 v93, v80
	v_fma_f32 v80, v99, s43, -v1
	v_add_f32_e32 v15, v90, v15
	v_exp_f32_e32 v99, v80
	v_fma_f32 v80, v101, s43, -v1
	v_add_f32_e32 v15, v91, v15
	v_exp_f32_e32 v101, v80
	v_fma_f32 v80, v103, s43, -v1
	v_add_f32_e32 v15, v92, v15
	v_exp_f32_e32 v103, v80
	v_fma_f32 v80, v104, s43, -v1
	v_add_f32_e32 v15, v93, v15
	v_exp_f32_e32 v81, v80
	v_fma_f32 v80, v102, s43, -v1
	v_add_f32_e32 v15, v99, v15
	v_exp_f32_e32 v82, v80
	v_fma_f32 v80, v100, s43, -v1
	v_add_f32_e32 v15, v101, v15
	v_exp_f32_e32 v83, v80
	v_fma_f32 v80, v98, s43, -v1
	v_sub_f32_e32 v14, v183, v1
	v_add_f32_e32 v15, v103, v15
	v_exp_f32_e32 v84, v80
	v_fma_f32 v80, v97, s43, -v1
	v_add_f32_e32 v15, v81, v15
	v_exp_f32_e32 v85, v80
	v_fma_f32 v80, v96, s43, -v1
	v_exp_f32_e32 v14, v14
	v_add_f32_e32 v15, v82, v15
	v_exp_f32_e32 v86, v80
	v_fma_f32 v80, v95, s43, -v1
	v_add_f32_e32 v15, v83, v15
	v_exp_f32_e32 v87, v80
	v_fma_f32 v80, v94, s43, -v1
	v_add_f32_e32 v15, v84, v15
	v_exp_f32_e32 v88, v80
	v_add_f32_e32 v15, v85, v15
	v_cmp_neq_f32_e32 vcc, 1.0, v14
	v_add_f32_e32 v15, v86, v15
	s_cmp_lg_u64 vcc, 0
	v_add_f32_e32 v15, v87, v15
	s_cselect_b64 s[36:37], -1, 0
	v_add_f32_e32 v15, v88, v15
	v_cndmask_b32_e64 v94, 0, 1, s[36:37]
	v_mov_b32_e32 v80, v15
	v_readfirstlane_b32 s33, v94
	s_bitcmp0_b32 s33, 0
	v_permlane32_swap_b32_e32 v15, v80
	s_cbranch_scc1 .LBB0_589
	v_pk_mul_f32 v[78:79], v[78:79], v[14:15] op_sel_hi:[1,0]
	v_pk_mul_f32 v[76:77], v[76:77], v[14:15] op_sel_hi:[1,0]
	v_pk_mul_f32 v[74:75], v[74:75], v[14:15] op_sel_hi:[1,0]
	v_pk_mul_f32 v[72:73], v[72:73], v[14:15] op_sel_hi:[1,0]
	v_pk_mul_f32 v[70:71], v[70:71], v[14:15] op_sel_hi:[1,0]
	v_pk_mul_f32 v[68:69], v[68:69], v[14:15] op_sel_hi:[1,0]
	v_pk_mul_f32 v[66:67], v[66:67], v[14:15] op_sel_hi:[1,0]
	v_pk_mul_f32 v[64:65], v[64:65], v[14:15] op_sel_hi:[1,0]
	v_pk_mul_f32 v[62:63], v[62:63], v[14:15] op_sel_hi:[1,0]
	v_pk_mul_f32 v[60:61], v[60:61], v[14:15] op_sel_hi:[1,0]
	v_pk_mul_f32 v[58:59], v[58:59], v[14:15] op_sel_hi:[1,0]
	v_pk_mul_f32 v[56:57], v[56:57], v[14:15] op_sel_hi:[1,0]
	v_pk_mul_f32 v[54:55], v[54:55], v[14:15] op_sel_hi:[1,0]
	v_pk_mul_f32 v[52:53], v[52:53], v[14:15] op_sel_hi:[1,0]
	v_pk_mul_f32 v[50:51], v[50:51], v[14:15] op_sel_hi:[1,0]
	v_pk_mul_f32 v[48:49], v[48:49], v[14:15] op_sel_hi:[1,0]
	v_pk_mul_f32 v[46:47], v[46:47], v[14:15] op_sel_hi:[1,0]
	v_pk_mul_f32 v[44:45], v[44:45], v[14:15] op_sel_hi:[1,0]
	v_pk_mul_f32 v[42:43], v[42:43], v[14:15] op_sel_hi:[1,0]
	v_pk_mul_f32 v[40:41], v[40:41], v[14:15] op_sel_hi:[1,0]
	v_pk_mul_f32 v[38:39], v[38:39], v[14:15] op_sel_hi:[1,0]
	v_pk_mul_f32 v[36:37], v[36:37], v[14:15] op_sel_hi:[1,0]
	v_pk_mul_f32 v[34:35], v[34:35], v[14:15] op_sel_hi:[1,0]
	v_pk_mul_f32 v[32:33], v[32:33], v[14:15] op_sel_hi:[1,0]
	v_pk_mul_f32 v[30:31], v[30:31], v[14:15] op_sel_hi:[1,0]
	v_pk_mul_f32 v[28:29], v[28:29], v[14:15] op_sel_hi:[1,0]
	v_pk_mul_f32 v[26:27], v[26:27], v[14:15] op_sel_hi:[1,0]
	v_pk_mul_f32 v[24:25], v[24:25], v[14:15] op_sel_hi:[1,0]
	v_pk_mul_f32 v[22:23], v[22:23], v[14:15] op_sel_hi:[1,0]
	v_pk_mul_f32 v[20:21], v[20:21], v[14:15] op_sel_hi:[1,0]
	v_pk_mul_f32 v[18:19], v[18:19], v[14:15] op_sel_hi:[1,0]
	v_pk_mul_f32 v[16:17], v[16:17], v[14:15] op_sel_hi:[1,0]

; __device__ __forceinline__ void attn_tile(const LAS bf16_t* kl, unsigned vaddr, int kt, const bf16x8 (&qf)[8], f32x16 (&o)[4], float& mrun, float& lrun, int r, int h, int rr, int p, int hd, size_t qtok,
;                                           bf16_t* __restrict__ OP, float* __restrict__ LSE) {
;     ...
;     float mx = fmaxf(fmaxf(s[0], s[1]), fmaxf(s[2], s[3]));
; #pragma unroll
;     for (int i = 4; i < 16; i += 4) mx = fmaxf(mx, fmaxf(fmaxf(s[i], s[i + 1]), fmaxf(s[i + 2], s[i + 3])));
;     { const auto pr = __builtin_amdgcn_permlane32_swap(__float_as_uint(mx), __float_as_uint(mx), false, false); mx = fmaxf(__uint_as_float(pr[0]), __uint_as_float(pr[1])); }
;     const float mnew = fmaxf(mrun, mx * scl);
;     const float alpha = __builtin_amdgcn_exp2f(mrun - mnew);
;     float rs = 0.f;
; #pragma unroll
;     for (int i = 0; i < 16; ++i) { s[i] = __builtin_amdgcn_exp2f(__builtin_fmaf(s[i], scl, -mnew)); rs += s[i]; }
;     { const auto pr = __builtin_amdgcn_permlane32_swap(__float_as_uint(rs), __float_as_uint(rs), false, false); rs = __uint_as_float(pr[0]) + __uint_as_float(pr[1]); }
;     lrun = lrun * alpha + rs; mrun = mnew;
;     if (__builtin_amdgcn_readfirstlane(__any(alpha != 1.0f) ? 1 : 0)) {
; #pragma unroll
;         for (int dt = 0; dt < 4; ++dt)
; #pragma unroll
;             for (int i = 0; i < 16; ++i) o[dt][i] *= alpha;
;     }
.LBB0_609:
	v_max3_f32 v1, v108, v109, v106
	v_max3_f32 v14, v107, v103, v101
	v_max3_f32 v15, v105, v99, v98
	v_max3_f32 v80, v100, v94, v95
	v_max3_f32 v1, v1, v104, v102
	v_max3_f32 v14, v14, v97, v96
	v_max3_f32 v1, v1, v14, v15
	v_max_f32_e32 v1, v1, v80
	v_mov_b32_e32 v14, v1
	s_nop 1
	v_permlane32_swap_b32_e32 v1, v14
	v_max_f32_e32 v1, v1, v14
	v_mul_f32_e32 v1, 0x3e0293ee, v1
	v_max_f32_e32 v14, v183, v183
	v_add_f32_e32 v80, 0x41000000, v14
	v_cmp_gt_f32_e32 vcc, v1, v80
	s_nop 1
	v_cndmask_b32_e32 v1, v14, v1, vcc
	v_fma_f32 v14, v109, s43, -v1
	v_exp_f32_e32 v89, v14
	v_fma_f32 v80, v108, s43, -v1
	v_exp_f32_e32 v90, v80
	v_fma_f32 v80, v107, s43, -v1
	v_exp_f32_e32 v91, v80
	v_fma_f32 v80, v106, s43, -v1
	v_exp_f32_e32 v92, v80
	v_fma_f32 v80, v105, s43, -v1
	v_add_f32_e32 v15, 0, v89
	v_exp_f32_e32 v93, v80
	v_fma_f32 v80, v99, s43, -v1
	v_add_f32_e32 v15, v90, v15
	v_exp_f32_e32 v99, v80
	v_fma_f32 v80, v101, s43, -v1
	v_add_f32_e32 v15, v91, v15
	v_exp_f32_e32 v101, v80
	v_fma_f32 v80, v103, s43, -v1
	v_add_f32_e32 v15, v92, v15
	v_exp_f32_e32 v103, v80
	v_fma_f32 v80, v104, s43, -v1
	v_add_f32_e32 v15, v93, v15
	v_exp_f32_e32 v81, v80
	v_fma_f32 v80, v102, s43, -v1
	v_add_f32_e32 v15, v99, v15
	v_exp_f32_e32 v82, v80
	v_fma_f32 v80, v100, s43, -v1
	v_add_f32_e32 v15, v101, v15
	v_exp_f32_e32 v83, v80
	v_fma_f32 v80, v98, s43, -v1
	v_sub_f32_e32 v14, v183, v1
	v_add_f32_e32 v15, v103, v15
	v_exp_f32_e32 v84, v80
	v_fma_f32 v80, v97, s43, -v1
	v_add_f32_e32 v15, v81, v15
	v_exp_f32_e32 v85, v80
	v_fma_f32 v80, v96, s43, -v1
	v_exp_f32_e32 v14, v14
	v_add_f32_e32 v15, v82, v15
	v_exp_f32_e32 v86, v80
	v_fma_f32 v80, v95, s43, -v1
	v_add_f32_e32 v15, v83, v15
	v_exp_f32_e32 v87, v80
	v_fma_f32 v80, v94, s43, -v1
	v_add_f32_e32 v15, v84, v15
	v_exp_f32_e32 v88, v80
	v_add_f32_e32 v15, v85, v15
	v_cmp_neq_f32_e32 vcc, 1.0, v14
	v_add_f32_e32 v15, v86, v15
	s_cmp_lg_u64 vcc, 0
	v_add_f32_e32 v15, v87, v15
	s_cselect_b64 s[38:39], -1, 0
	v_add_f32_e32 v15, v88, v15
	v_cndmask_b32_e64 v94, 0, 1, s[38:39]
	v_mov_b32_e32 v80, v15
	v_readfirstlane_b32 s33, v94
	s_bitcmp0_b32 s33, 0
	v_permlane32_swap_b32_e32 v15, v80
	s_cbranch_scc1 .LBB0_611
	v_pk_mul_f32 v[78:79], v[78:79], v[14:15] op_sel_hi:[1,0]
	v_pk_mul_f32 v[76:77], v[76:77], v[14:15] op_sel_hi:[1,0]
	v_pk_mul_f32 v[74:75], v[74:75], v[14:15] op_sel_hi:[1,0]
	v_pk_mul_f32 v[72:73], v[72:73], v[14:15] op_sel_hi:[1,0]
	v_pk_mul_f32 v[70:71], v[70:71], v[14:15] op_sel_hi:[1,0]
	v_pk_mul_f32 v[68:69], v[68:69], v[14:15] op_sel_hi:[1,0]
	v_pk_mul_f32 v[66:67], v[66:67], v[14:15] op_sel_hi:[1,0]
	v_pk_mul_f32 v[64:65], v[64:65], v[14:15] op_sel_hi:[1,0]
	v_pk_mul_f32 v[62:63], v[62:63], v[14:15] op_sel_hi:[1,0]
	v_pk_mul_f32 v[60:61], v[60:61], v[14:15] op_sel_hi:[1,0]
	v_pk_mul_f32 v[58:59], v[58:59], v[14:15] op_sel_hi:[1,0]
	v_pk_mul_f32 v[56:57], v[56:57], v[14:15] op_sel_hi:[1,0]
	v_pk_mul_f32 v[54:55], v[54:55], v[14:15] op_sel_hi:[1,0]
	v_pk_mul_f32 v[52:53], v[52:53], v[14:15] op_sel_hi:[1,0]
	v_pk_mul_f32 v[50:51], v[50:51], v[14:15] op_sel_hi:[1,0]
	v_pk_mul_f32 v[48:49], v[48:49], v[14:15] op_sel_hi:[1,0]
	v_pk_mul_f32 v[46:47], v[46:47], v[14:15] op_sel_hi:[1,0]
	v_pk_mul_f32 v[44:45], v[44:45], v[14:15] op_sel_hi:[1,0]
	v_pk_mul_f32 v[42:43], v[42:43], v[14:15] op_sel_hi:[1,0]
	v_pk_mul_f32 v[40:41], v[40:41], v[14:15] op_sel_hi:[1,0]
	v_pk_mul_f32 v[38:39], v[38:39], v[14:15] op_sel_hi:[1,0]
	v_pk_mul_f32 v[36:37], v[36:37], v[14:15] op_sel_hi:[1,0]
	v_pk_mul_f32 v[34:35], v[34:35], v[14:15] op_sel_hi:[1,0]
	v_pk_mul_f32 v[32:33], v[32:33], v[14:15] op_sel_hi:[1,0]
	v_pk_mul_f32 v[30:31], v[30:31], v[14:15] op_sel_hi:[1,0]
	v_pk_mul_f32 v[28:29], v[28:29], v[14:15] op_sel_hi:[1,0]
	v_pk_mul_f32 v[26:27], v[26:27], v[14:15] op_sel_hi:[1,0]
	v_pk_mul_f32 v[24:25], v[24:25], v[14:15] op_sel_hi:[1,0]
	v_pk_mul_f32 v[22:23], v[22:23], v[14:15] op_sel_hi:[1,0]
	v_pk_mul_f32 v[20:21], v[20:21], v[14:15] op_sel_hi:[1,0]
	v_pk_mul_f32 v[18:19], v[18:19], v[14:15] op_sel_hi:[1,0]
	v_pk_mul_f32 v[16:17], v[16:17], v[14:15] op_sel_hi:[1,0]
